# phase D: ssd_p2 queue items halved (4 tasks per item, 1024 items) to shorten the phase tail
# speedup vs baseline: 1.0112x; 1.0110x over previous
.LBB0_292:
	s_or_b64 exec, exec, s[0:1]
	s_waitcnt lgkmcnt(0)
	s_barrier
	ds_read_b32 v1, v161
	s_waitcnt lgkmcnt(0)
	v_readfirstlane_b32 s14, v1
	s_cmpk_gt_i32 s14, 0x83f
	s_cbranch_scc1 .LBB0_398
	v_readlane_b32 s0, v254, 51
	s_lshl_b32 s90, s0, 9
	s_ashr_i32 s91, s90, 31
	s_branch .LBB0_296

.LBB0_295:
	s_or_b64 exec, exec, s[2:3]
	s_waitcnt lgkmcnt(0)
	s_barrier
	ds_read_b32 v1, v161
	s_waitcnt lgkmcnt(0)
	v_readfirstlane_b32 s14, v1
	s_cmpk_gt_i32 s14, 0x83f
	s_cbranch_scc1 .LBB0_398
.LBB0_296:
	s_cmpk_gt_i32 s14, 0x21f
	s_mov_b64 s[2:3], -1
	s_cbranch_scc0 .LBB0_328
	s_cmpk_lt_u32 s14, 0x440
	s_cbranch_scc1 .LBB0_323
	s_lshl_b32 s15, s14, 2
	s_addk_i32 s15, 0xef00
	s_mov_b32 s16, 0
	s_branch .LBB0_300
.LBB0_299:
	s_add_i32 s16, s16, 1
	s_cmp_lg_u32 s16, 4
	s_cbranch_scc0 .LBB0_322
